# XCD-local barriers (own code, run-time checked block-to-XCD mapping) replace the grid barrier for the phase 6->7 and 7->8 transitions
# speedup vs baseline: 1.0092x; 1.0050x over previous
_Z8fwd_mega6Paramsii:
	s_mov_b32 s95, 0
	s_load_dwordx2 s[52:53], s[0:1], 0x130
	s_add_u32 s6, s0, 0x130
	v_and_b32_e32 v168, 0x3ff, v0
	s_addc_u32 s7, s1, 0
	v_cmp_eq_u32_e64 s[4:5], 0, v168
	s_and_saveexec_b64 s[8:9], s[4:5]
	v_mov_b32_e32 v2, 0
	v_mov_b32_e32 v3, v2
	v_mov_b32_e32 v4, v2
	v_mov_b32_e32 v5, v2
	ds_write_b128 v2, v[2:5]
	s_or_b64 exec, exec, s[8:9]
	s_load_dword s78, s[0:1], 0x138
	s_load_dwordx2 s[46:47], s[0:1], 0x120
	s_waitcnt lgkmcnt(0)
	s_barrier
	s_getreg_b32 s3, hwreg(HW_REG_XCC_ID, 0, 4)
	s_and_b32 s33, s3, 15
	s_and_saveexec_b64 s[8:9], s[4:5]
	s_cbranch_execz .LBB0_5
	s_mov_b64 s[10:11], exec
	v_mbcnt_lo_u32_b32 v1, s10, 0
	v_mbcnt_hi_u32_b32 v1, s11, v1
	v_cmp_eq_u32_e32 vcc, 0, v1
	s_and_b64 s[12:13], exec, vcc
	s_mov_b64 exec, s[12:13]
	s_cbranch_execz .LBB0_5
	s_lshl_b32 s3, s33, 8
	s_bcnt1_i32_b64 s10, s[10:11]
	v_mov_b32_e32 v1, s3
	v_mov_b32_e32 v2, s10
	global_atomic_add v1, v2, s[46:47] offset:1024
	s_and_b32 s3, s2, 7
	s_lshl_b32 s3, s3, 8
	s_add_u32 s3, s3, 0x480
	v_mov_b32_e32 v3, s3
	s_lshl_b32 s10, 1, s33
	v_mov_b32_e32 v4, s10
	global_atomic_or v3, v4, s[46:47]

.LBB0_475:
	s_cmp_gt_i32 s55, 7
	s_cbranch_scc0 .LBB0_529
	s_waitcnt vmcnt(0) lgkmcnt(0)
	s_barrier
	v_mov_b32_e32 v0, 8
	ds_read_b32 v1, v0
	s_waitcnt lgkmcnt(0)
	v_readfirstlane_b32 s3, v1
	s_nop 3
	s_barrier
	s_cmp_lg_u32 s3, 0
	s_cbranch_scc1 .Lxl67_have
	s_and_saveexec_b64 s[6:7], s[4:5]
	s_cbranch_execz .Lxl67_m1
	v_mov_b32_e32 v0, 0
	global_load_dword v1, v0, s[46:47] offset:1152 sc1
	global_load_dword v2, v0, s[46:47] offset:1408 sc1
	global_load_dword v3, v0, s[46:47] offset:1664 sc1
	global_load_dword v4, v0, s[46:47] offset:1920 sc1
	global_load_dword v5, v0, s[46:47] offset:2176 sc1
	global_load_dword v6, v0, s[46:47] offset:2432 sc1
	global_load_dword v7, v0, s[46:47] offset:2688 sc1
	global_load_dword v8, v0, s[46:47] offset:2944 sc1
	s_waitcnt vmcnt(0)
	v_or3_b32 v9, v1, v2, v3
	v_or3_b32 v9, v9, v4, v5
	v_or3_b32 v9, v9, v6, v7
	v_or_b32_e32 v9, v9, v8
	v_mov_b32_e32 v11, 0
	v_add_u32_e32 v10, -1, v1
	v_and_b32_e32 v10, v10, v1
	v_or_b32_e32 v11, v11, v10
	v_add_u32_e32 v10, -1, v2
	v_and_b32_e32 v10, v10, v2
	v_or_b32_e32 v11, v11, v10
	v_add_u32_e32 v10, -1, v3
	v_and_b32_e32 v10, v10, v3
	v_or_b32_e32 v11, v11, v10
	v_add_u32_e32 v10, -1, v4
	v_and_b32_e32 v10, v10, v4
	v_or_b32_e32 v11, v11, v10
	v_add_u32_e32 v10, -1, v5
	v_and_b32_e32 v10, v10, v5
	v_or_b32_e32 v11, v11, v10
	v_add_u32_e32 v10, -1, v6
	v_and_b32_e32 v10, v10, v6
	v_or_b32_e32 v11, v11, v10
	v_add_u32_e32 v10, -1, v7
	v_and_b32_e32 v10, v10, v7
	v_or_b32_e32 v11, v11, v10
	v_add_u32_e32 v10, -1, v8
	v_and_b32_e32 v10, v10, v8
	v_or_b32_e32 v11, v11, v10
	s_nop 1
	v_readfirstlane_b32 s8, v9
	v_readfirstlane_b32 s9, v11
	s_nop 3
	s_cmp_eq_u32 s8, 0xff
	s_cselect_b32 s11, 1, 0
	s_cmp_eq_u32 s9, 0
	s_cselect_b32 s11, s11, 0
	s_cmp_eq_u32 s52, 0x200
	s_cselect_b32 s11, s11, 0
	s_cmp_eq_u32 s11, 1
	s_cselect_b32 s10, 1, 2
	v_mov_b32_e32 v0, 8
	v_mov_b32_e32 v1, s10
	ds_write_b32 v0, v1
	s_waitcnt lgkmcnt(0)
.Lxl67_m1:
	s_or_b64 exec, exec, s[6:7]
	s_barrier
	v_mov_b32_e32 v0, 8
	ds_read_b32 v1, v0
	s_waitcnt lgkmcnt(0)
	v_readfirstlane_b32 s3, v1
	s_nop 3
.Lxl67_have:
	s_cmp_eq_u32 s3, 1
	s_cbranch_scc0 .Lxl67_orig
	s_and_saveexec_b64 s[6:7], s[4:5]
	s_cbranch_execz .Lxl67_w
	s_and_b32 s8, s2, 7
	s_lshl_b32 s8, s8, 8
	s_add_u32 s10, s46, s8
	s_addc_u32 s11, s47, 0
	s_add_u32 s12, s10, 0x2480
	s_addc_u32 s13, s11, 0
	s_add_u32 s10, s10, 0x1480
	s_addc_u32 s11, s11, 0
	v_mov_b32_e32 v0, 0
	v_mov_b32_e32 v1, 1
	global_atomic_add v2, v0, v1, s[10:11] sc0
	s_waitcnt vmcnt(0)
	v_readfirstlane_b32 s3, v2
	s_nop 3
	s_lshr_b32 s14, s3, 6
	s_and_b32 s3, s3, 63
	s_cmp_eq_u32 s3, 63
	s_cbranch_scc0 .Lxl67_spin
	global_atomic_add v0, v1, s[12:13]
	s_waitcnt vmcnt(0)
	s_branch .Lxl67_acq
.Lxl67_spin:
	s_sleep 1
	global_load_dword v2, v0, s[12:13] sc1
	s_waitcnt vmcnt(0)
	v_readfirstlane_b32 s3, v2
	s_nop 3
	s_cmp_eq_u32 s3, s14
	s_cbranch_scc1 .Lxl67_spin
.Lxl67_acq:
	buffer_inv sc1
	s_waitcnt vmcnt(0)
.Lxl67_w:
	s_or_b64 exec, exec, s[6:7]
	s_barrier
	s_branch .LBB0_529
.Lxl67_orig:
	s_waitcnt vmcnt(0)
	s_waitcnt vmcnt(0)
	s_barrier
	s_and_saveexec_b64 s[6:7], s[4:5]
	s_cbranch_execz .LBB0_528
	v_mov_b32_e32 v16, 0
	s_waitcnt vmcnt(0) expcnt(0) lgkmcnt(0)
	ds_read_b32 v2, v16
	ds_read_b32 v0, v16 offset:4
	s_waitcnt lgkmcnt(1)
	v_cmp_ne_u32_e32 vcc, 0, v2
	s_cbranch_vccnz .LBB0_492
	s_add_u32 s8, s46, 0x1000
	s_addc_u32 s9, s47, 0
	s_add_u32 s10, s46, 0x1100
	s_addc_u32 s11, s47, 0
	s_add_u32 s12, s46, 0x1200
	s_addc_u32 s13, s47, 0
	s_mul_i32 s3, s53, s78
	s_add_u32 s14, s46, 0x1300
	s_mul_i32 s3, s3, s52
	s_addc_u32 s15, s47, 0
	s_mov_b32 s22, 1
	s_branch .LBB0_480

.LBB0_543:
	s_cmp_lt_i32 s55, 9
	s_cbranch_scc1 .LBB0_597
	s_waitcnt vmcnt(0) lgkmcnt(0)
	s_barrier
	v_mov_b32_e32 v0, 8
	ds_read_b32 v1, v0
	s_waitcnt lgkmcnt(0)
	v_readfirstlane_b32 s3, v1
	s_nop 3
	s_barrier
	s_cmp_lg_u32 s3, 0
	s_cbranch_scc1 .Lxl78_have
	s_and_saveexec_b64 s[6:7], s[4:5]
	s_cbranch_execz .Lxl78_m1
	v_mov_b32_e32 v0, 0
	global_load_dword v1, v0, s[46:47] offset:1152 sc1
	global_load_dword v2, v0, s[46:47] offset:1408 sc1
	global_load_dword v3, v0, s[46:47] offset:1664 sc1
	global_load_dword v4, v0, s[46:47] offset:1920 sc1
	global_load_dword v5, v0, s[46:47] offset:2176 sc1
	global_load_dword v6, v0, s[46:47] offset:2432 sc1
	global_load_dword v7, v0, s[46:47] offset:2688 sc1
	global_load_dword v8, v0, s[46:47] offset:2944 sc1
	s_waitcnt vmcnt(0)
	v_or3_b32 v9, v1, v2, v3
	v_or3_b32 v9, v9, v4, v5
	v_or3_b32 v9, v9, v6, v7
	v_or_b32_e32 v9, v9, v8
	v_mov_b32_e32 v11, 0
	v_add_u32_e32 v10, -1, v1
	v_and_b32_e32 v10, v10, v1
	v_or_b32_e32 v11, v11, v10
	v_add_u32_e32 v10, -1, v2
	v_and_b32_e32 v10, v10, v2
	v_or_b32_e32 v11, v11, v10
	v_add_u32_e32 v10, -1, v3
	v_and_b32_e32 v10, v10, v3
	v_or_b32_e32 v11, v11, v10
	v_add_u32_e32 v10, -1, v4
	v_and_b32_e32 v10, v10, v4
	v_or_b32_e32 v11, v11, v10
	v_add_u32_e32 v10, -1, v5
	v_and_b32_e32 v10, v10, v5
	v_or_b32_e32 v11, v11, v10
	v_add_u32_e32 v10, -1, v6
	v_and_b32_e32 v10, v10, v6
	v_or_b32_e32 v11, v11, v10
	v_add_u32_e32 v10, -1, v7
	v_and_b32_e32 v10, v10, v7
	v_or_b32_e32 v11, v11, v10
	v_add_u32_e32 v10, -1, v8
	v_and_b32_e32 v10, v10, v8
	v_or_b32_e32 v11, v11, v10
	s_nop 1
	v_readfirstlane_b32 s8, v9
	v_readfirstlane_b32 s9, v11
	s_nop 3
	s_cmp_eq_u32 s8, 0xff
	s_cselect_b32 s11, 1, 0
	s_cmp_eq_u32 s9, 0
	s_cselect_b32 s11, s11, 0
	s_cmp_eq_u32 s52, 0x200
	s_cselect_b32 s11, s11, 0
	s_cmp_eq_u32 s11, 1
	s_cselect_b32 s10, 1, 2
	v_mov_b32_e32 v0, 8
	v_mov_b32_e32 v1, s10
	ds_write_b32 v0, v1
	s_waitcnt lgkmcnt(0)
